# R2/R3 row passes: fast iteration body (both rows active) with all x/Y/modulation loads batched up front, gpost/gpre in regs, DPP row sums, counted vmcnt; compiler body kept as slow path
# speedup vs baseline: 1.0332x; 1.0218x over previous
;     __device__ __forceinline__ void init(int N, int G, int c, int latent_only) { lat = latent_only; b.init(latent_only ? NB * SEQ : M, N, G, c); }
;     __device__ __forceinline__ void init(int c_, unsigned* cnt_) { lat.init(NB * SEQ, FF2, 1, 0); c = c_; cnt = cnt_; }
; __device__ __forceinline__ void row_pass(const RowPass& R, int gw, int ngw, int lane) {
;     constexpr int NR = 2;
;     for (int row0 = gw; row0 < M; row0 += NR * ngw) {
;         f32x4 v[NR][4]; u32x2 yw[NR][4]; bool act[NR]; float* xrow[NR]; int bbs[NR];
; #pragma unroll
;         for (int k = 0; k < NR; ++k) {
;             const int row = row0 + k * ngw;
;             const int rowc = row < M ? row : row0;
;             const int b = rowc / RPB, i = rowc - b * RPB; const bool isctx = i < CTXL;
;             act[k] = (row < M) && !(isctx && R.skip_ctx);
;             bbs[k] = isctx ? 8 : b;
;             xrow[k] = isctx ? R.xc + ((size_t)b * CTXL + i) * DM : R.out + ((size_t)b * SEQ + (i - CTXL)) * DM;
;             const float* src = R.init ? (isctx ? R.ctx_in + ((size_t)b * CTXL + i) * DM : R.x_in + ((size_t)b * SEQ + (i - CTXL)) * DM) : xrow[k];
;             if (act[k]) {
; #pragma unroll
;                 for (int j = 0; j < 4; ++j) v[k][j] = __builtin_nontemporal_load((const f32x4*)(src + lane * 4 + 256 * j));
; __global__ void __launch_bounds__(NTHR, 2) fwd_kernel(Args A_) {
;     ...
;             } else if (s == 3) {
;                 RowPass R{A->x, A->ctx, A->out, xc, Yb, Hb, modp, A->g_post_mix + l * DM, A->g_pre_ffn + l * DM, 0, 1, 1, l, 2, l, 3, l == DEPTH - 1};
;                 row_pass(R, gw, ngw, lane);
.LBB0_128:
	s_cmp_gt_i32 s84, 2
	s_mov_b64 s[4:5], -1
	s_cbranch_scc0 .LBB0_141
	s_cmp_gt_i32 s36, 0x87ff
	s_cbranch_scc1 .LBB0_140
	s_sub_i32 s3, s57, 30
	s_load_dwordx2 s[4:5], s[0:1], 0xa0
	s_load_dwordx4 s[8:11], s[0:1], 0x38
	s_cmp_lt_u32 s3, -7
	s_cselect_b64 s[62:63], -1, 0
	s_lshl_b32 s6, s12, 10
	s_ashr_i32 s7, s6, 31
	s_lshl_b64 s[6:7], s[6:7], 2
	s_waitcnt lgkmcnt(0)
	s_add_u32 s10, s10, s6
	s_addc_u32 s11, s11, s7
	s_add_u32 s6, s8, s6
	s_addc_u32 s7, s9, s7
	s_waitcnt vmcnt(0)
	v_lshlrev_b32_e32 v0, 4, v216
	v_mov_b32_e32 v1, v161
	s_ashr_i32 s37, s36, 31
	v_lshl_add_u64 v[42:43], s[6:7], 0, v[0:1]
	s_lshl_b64 s[6:7], s[36:37], 11
	s_add_u32 s6, s28, s6
	v_lshlrev_b32_e32 v160, 3, v216
	s_addc_u32 s7, s29, s7
	v_lshl_add_u64 v[44:45], s[10:11], 0, v[0:1]
	v_lshl_add_u64 v[0:1], s[6:7], 0, v[160:161]
	s_mov_b64 s[6:7], 0xa7fa600
	v_lshlrev_b32_e32 v36, 2, v216
	v_lshl_add_u64 v[38:39], s[20:21], 0, v[160:161]
	v_lshl_add_u64 v[40:41], s[60:61], 0, v[160:161]
	s_mul_i32 s3, s12, 9
	v_lshl_add_u64 v[46:47], v[0:1], 0, s[6:7]
	global_load_dwordx4 v[218:221], v[42:43], off
	global_load_dwordx4 v[222:225], v[42:43], off offset:1024
	global_load_dwordx4 v[226:229], v[42:43], off offset:2048
	global_load_dwordx4 v[230:233], v[42:43], off offset:3072
	global_load_dwordx4 v[234:237], v[44:45], off
	global_load_dwordx4 v[238:241], v[44:45], off offset:1024
	global_load_dwordx4 v[242:245], v[44:45], off offset:2048
	global_load_dwordx4 v[246:249], v[44:45], off offset:3072
	s_mov_b32 s13, s36
	s_branch .LBB0_132

; __device__ __forceinline__ float bflo(unsigned w) { return __uint_as_float(w << 16); }
; __device__ __forceinline__ float bfhi(unsigned w) { return __uint_as_float(w & 0xffff0000u); }
; __device__ __forceinline__ void row_pass(const RowPass& R, int gw, int ngw, int lane) {
;     ...
;     for (int row0 = gw; row0 < M; row0 += NR * ngw) {
;         f32x4 v[NR][4]; u32x2 yw[NR][4]; bool act[NR]; float* xrow[NR]; int bbs[NR];
; #pragma unroll
;         for (int k = 0; k < NR; ++k) {
;             const int row = row0 + k * ngw;
;             const int rowc = row < M ? row : row0;
;             const int b = rowc / RPB, i = rowc - b * RPB; const bool isctx = i < CTXL;
;             act[k] = (row < M) && !(isctx && R.skip_ctx);
;             bbs[k] = isctx ? 8 : b;
;             xrow[k] = isctx ? R.xc + ((size_t)b * CTXL + i) * DM : R.out + ((size_t)b * SEQ + (i - CTXL)) * DM;
;             const float* src = R.init ? (isctx ? R.ctx_in + ((size_t)b * CTXL + i) * DM : R.x_in + ((size_t)b * SEQ + (i - CTXL)) * DM) : xrow[k];
;             if (act[k]) {
; #pragma unroll
;                 for (int j = 0; j < 4; ++j) v[k][j] = __builtin_nontemporal_load((const f32x4*)(src + lane * 4 + 256 * j));
;                 if (R.update) { const bf16* yr = R.Y + (size_t)rowc * DM;
; #pragma unroll
;                     for (int j = 0; j < 4; ++j) yw[k][j] = __builtin_nontemporal_load((const u32x2*)(yr + lane * 4 + 256 * j)); }
;             }
;         }
; #pragma unroll
;         for (int k = 0; k < NR; ++k) {
;             if (!act[k]) continue;
;             const int row = row0 + k * ngw, bb = bbs[k];
;             if (R.update) {
;                 f32x4 y[4]; float ss = 0.f;
; #pragma unroll
;                 for (int j = 0; j < 4; ++j) { const u32x2 w = yw[k][j]; y[j] = (f32x4){bflo(w.x), bfhi(w.x), bflo(w.y), bfhi(w.y)};
;                     ss += (y[j][0] * y[j][0] + y[j][1] * y[j][1]) + (y[j][2] * y[j][2] + y[j][3] * y[j][3]); }
;                 const float rstd = __builtin_amdgcn_rsqf(wave_sum(ss) * (1.0f / DM) + EPS);
;                 const float* gate = R.mod + ((size_t)(R.lg * 9 + bb) * NMOD + R.gi) * DM;
; #pragma unroll
;                 for (int j = 0; j < 4; ++j) { const f32x4 g = *(const f32x4*)(gate + lane * 4 + 256 * j), gp = *(const f32x4*)(R.gpost + lane * 4 + 256 * j);
;                     v[k][j] = v[k][j] + g * (y[j] * rstd * gp); }
.LBB0_132:
	s_mul_hi_i32 s6, s13, 0x78787879
	s_lshr_b32 s7, s6, 31
	s_ashr_i32 s6, s6, 11
	s_add_i32 s6, s6, s7
	s_mul_i32 s7, s6, 0xffffef00
	s_add_i32 s7, s13, s7
	s_cmpk_gt_i32 s7, 0xff
	s_cselect_b64 s[50:51], -1, 0
	s_add_i32 s8, s44, s13
	s_cmp_lt_i32 s8, 0x8800
	s_cbranch_scc0 .Lr2_slow
	s_mul_hi_i32 s9, s8, 0x78787879
	s_lshr_b32 s25, s9, 31
	s_ashr_i32 s9, s9, 11
	s_add_i32 s9, s9, s25
	s_mul_i32 s25, s9, 0xffffef00
	s_add_i32 s25, s8, s25
	s_cmpk_gt_i32 s25, 0xff
	s_cselect_b64 s[52:53], -1, 0
	s_and_b64 s[46:47], s[50:51], s[52:53]
	s_or_b64 s[46:47], s[46:47], s[62:63]
	s_cmp_lg_u64 s[46:47], 0
	s_cbranch_scc0 .Lr2_slow
	v_lshlrev_b32_e32 v160, 2, v36
	s_add_i32 s72, s7, 0xffffff00
	s_cmp_lg_u64 s[50:51], 0
	s_cselect_b32 s27, s4, s49
	s_cselect_b32 s32, s5, s55
	s_cselect_b32 s37, 24, 20
	s_cselect_b32 s72, s72, s7
	s_cselect_b32 s85, s6, 8
	s_mov_b32 s40, s6
	s_mov_b32 s41, 0
	s_lshl_b64 s[40:41], s[40:41], s37
	s_add_u32 s40, s27, s40
	s_addc_u32 s41, s32, s41
	s_lshl_b32 s72, s72, 12
	s_add_u32 s40, s40, s72
	s_addc_u32 s41, s41, 0
	s_add_i32 s27, s85, s3
	s_mul_hi_i32 s32, s27, 0x6000
	s_mulk_i32 s27, 0x6000
	s_add_u32 s66, s34, s27
	s_addc_u32 s67, s35, s32
	s_add_u32 s66, s66, 0x2000
	s_addc_u32 s67, s67, 0
	s_add_i32 s27, s85, s3
	s_mul_hi_i32 s32, s27, 0x6000
	s_mulk_i32 s27, 0x6000
	s_add_u32 s38, s34, s27
	s_addc_u32 s39, s35, s32
	s_add_u32 s38, s38, 0x3000
	s_addc_u32 s39, s39, 0
	s_add_u32 s46, s38, 0x1000
	s_addc_u32 s47, s39, 0
	global_load_dwordx4 v[12:15], v160, s[40:41] nt
	global_load_dwordx4 v[8:11], v160, s[40:41] offset:1024 nt
	global_load_dwordx4 v[4:7], v160, s[40:41] offset:2048 nt
	global_load_dwordx4 v[0:3], v160, s[40:41] offset:3072 nt
	global_load_dwordx2 v[54:55], v[46:47], off offset:-1536 nt
	global_load_dwordx2 v[52:53], v[46:47], off offset:-1024 nt
	global_load_dwordx2 v[50:51], v[46:47], off offset:-512 nt
	global_load_dwordx2 v[48:49], v[46:47], off nt
	global_load_dwordx4 v[64:67], v160, s[66:67]
	global_load_dwordx4 v[68:71], v160, s[66:67] offset:1024
	global_load_dwordx4 v[72:75], v160, s[66:67] offset:2048
	global_load_dwordx4 v[76:79], v160, s[66:67] offset:3072
	s_mov_b32 s6, s8
	s_ashr_i32 s7, s8, 31
	s_lshl_b64 s[6:7], s[6:7], 11
	v_lshl_add_u64 v[250:251], v[38:39], 0, s[6:7]
	v_lshl_add_u64 v[252:253], v[40:41], 0, s[6:7]
	s_mov_b64 s[6:7], s[52:53]
	s_add_i32 s72, s25, 0xffffff00
	s_cmp_lg_u64 s[6:7], 0
	s_cselect_b32 s27, s4, s49
	s_cselect_b32 s32, s5, s55
	s_cselect_b32 s37, 24, 20
	s_cselect_b32 s72, s72, s25
	s_cselect_b32 s85, s9, 8
	s_mov_b32 s64, s9
	s_mov_b32 s65, 0
	s_lshl_b64 s[64:65], s[64:65], s37
	s_add_u32 s64, s27, s64
	s_addc_u32 s65, s32, s65
	s_lshl_b32 s72, s72, 12
	s_add_u32 s64, s64, s72
	s_addc_u32 s65, s65, 0
	s_add_i32 s27, s85, s3
	s_mul_hi_i32 s32, s27, 0x6000
	s_mulk_i32 s27, 0x6000
	s_add_u32 s10, s34, s27
	s_addc_u32 s11, s35, s32
	s_add_u32 s10, s10, 0x2000
	s_addc_u32 s11, s11, 0
	s_add_i32 s27, s85, s3
	s_mul_hi_i32 s32, s27, 0x6000
	s_mulk_i32 s27, 0x6000
	s_add_u32 s50, s34, s27
	s_addc_u32 s51, s35, s32
	s_add_u32 s50, s50, 0x3000
	s_addc_u32 s51, s51, 0
	s_add_u32 s52, s50, 0x1000
	s_addc_u32 s53, s51, 0
	global_load_dwordx4 v[16:19], v160, s[64:65] nt
	global_load_dwordx4 v[20:23], v160, s[64:65] offset:1024 nt
	global_load_dwordx4 v[24:27], v160, s[64:65] offset:2048 nt
	global_load_dwordx4 v[28:31], v160, s[64:65] offset:3072 nt
	global_load_dwordx2 v[62:63], v[250:251], off nt
	global_load_dwordx2 v[60:61], v[250:251], off offset:512 nt
	global_load_dwordx2 v[58:59], v[250:251], off offset:1024 nt
	global_load_dwordx2 v[56:57], v[250:251], off offset:1536 nt
	global_load_dwordx4 v[80:83], v160, s[38:39]
	global_load_dwordx4 v[84:87], v160, s[38:39] offset:1024
	global_load_dwordx4 v[88:91], v160, s[38:39] offset:2048
	global_load_dwordx4 v[92:95], v160, s[38:39] offset:3072
	global_load_dwordx4 v[172:175], v160, s[46:47]
	global_load_dwordx4 v[176:179], v160, s[46:47] offset:1024
	global_load_dwordx4 v[180:183], v160, s[46:47] offset:2048
	global_load_dwordx4 v[184:187], v160, s[46:47] offset:3072
	global_load_dwordx4 v[188:191], v160, s[10:11]
	global_load_dwordx4 v[192:195], v160, s[10:11] offset:1024
	global_load_dwordx4 v[196:199], v160, s[10:11] offset:2048
	global_load_dwordx4 v[96:99], v160, s[10:11] offset:3072
	s_waitcnt vmcnt(24)
	v_lshlrev_b32_e32 v32, 16, v54
	v_and_b32_e32 v33, 0xffff0000, v54
	v_lshlrev_b32_e32 v34, 16, v55
	v_and_b32_e32 v35, 0xffff0000, v55
	v_pk_mul_f32 v[166:167], v[32:33], v[32:33]
	v_pk_mul_f32 v[168:169], v[34:35], v[34:35]
	v_lshlrev_b32_e32 v32, 16, v52
	v_and_b32_e32 v33, 0xffff0000, v52
	v_lshlrev_b32_e32 v34, 16, v53
	v_and_b32_e32 v35, 0xffff0000, v53
	v_pk_fma_f32 v[166:167], v[32:33], v[32:33], v[166:167]
	v_pk_fma_f32 v[168:169], v[34:35], v[34:35], v[168:169]
	v_lshlrev_b32_e32 v32, 16, v50
	v_and_b32_e32 v33, 0xffff0000, v50
	v_lshlrev_b32_e32 v34, 16, v51
	v_and_b32_e32 v35, 0xffff0000, v51
	v_pk_fma_f32 v[166:167], v[32:33], v[32:33], v[166:167]
	v_pk_fma_f32 v[168:169], v[34:35], v[34:35], v[168:169]
	v_lshlrev_b32_e32 v32, 16, v48
	v_and_b32_e32 v33, 0xffff0000, v48
	v_lshlrev_b32_e32 v34, 16, v49
	v_and_b32_e32 v35, 0xffff0000, v49
	v_pk_fma_f32 v[166:167], v[32:33], v[32:33], v[166:167]
	v_pk_fma_f32 v[168:169], v[34:35], v[34:35], v[168:169]
	v_pk_add_f32 v[166:167], v[166:167], v[168:169]
	s_nop 0
	v_add_f32_e32 v164, v166, v167
	v_mov_b32_e32 v165, v164
	s_nop 1
	v_permlane32_swap_b32_e32 v165, v164
	v_add_f32_e32 v164, v164, v165
	v_mov_b32_e32 v165, v164
	s_nop 1
	v_permlane16_swap_b32_e32 v165, v164
	v_add_f32_e32 v164, v164, v165
	s_nop 1
	v_add_f32_dpp v164, v164, v164 row_ror:8 row_mask:0xf bank_mask:0xf
	s_nop 1
	v_add_f32_dpp v164, v164, v164 row_ror:4 row_mask:0xf bank_mask:0xf
	s_nop 1
	v_add_f32_dpp v164, v164, v164 row_ror:2 row_mask:0xf bank_mask:0xf
	s_nop 1
	v_add_f32_dpp v164, v164, v164 row_ror:1 row_mask:0xf bank_mask:0xf
	s_nop 0
	v_fmamk_f32 v164, v164, 0x3a800000, v200
	v_rsq_f32_e32 v164, v164
	v_lshlrev_b32_e32 v32, 16, v54
	v_and_b32_e32 v33, 0xffff0000, v54
	v_lshlrev_b32_e32 v34, 16, v55
	v_and_b32_e32 v35, 0xffff0000, v55
	v_pk_mul_f32 v[32:33], v[32:33], v[164:165] op_sel_hi:[1,0]
	v_pk_mul_f32 v[34:35], v[34:35], v[164:165] op_sel_hi:[1,0]
	v_pk_mul_f32 v[32:33], v[218:219], v[32:33]
	v_pk_mul_f32 v[34:35], v[220:221], v[34:35]
	s_waitcnt vmcnt(23)
; __device__ __forceinline__ unsigned pk2(float lo, float hi) { return pg8::cvt_pk_bf16(lo, hi); }
;     __device__ __forceinline__ void init(int N, int G, int c, int latent_only) { lat = latent_only; b.init(latent_only ? NB * SEQ : M, N, G, c); }
;     __device__ __forceinline__ void init(int c_, unsigned* cnt_) { lat.init(NB * SEQ, FF2, 1, 0); c = c_; cnt = cnt_; }
; __device__ __forceinline__ void row_pass(const RowPass& R, int gw, int ngw, int lane) {
;     ...
;                     v[k][j] = v[k][j] + g * (y[j] * rstd * gp); }
;             }
;             if (R.init || R.update) {
; #pragma unroll
;                 for (int j = 0; j < 4; ++j) __builtin_nontemporal_store(v[k][j], (f32x4*)(xrow[k] + lane * 4 + 256 * j));
;             }
;             if (R.norm_out) {
;                 float ss = 0.f;
; #pragma unroll
;                 for (int j = 0; j < 4; ++j) ss += (v[k][j][0] * v[k][j][0] + v[k][j][1] * v[k][j][1]) + (v[k][j][2] * v[k][j][2] + v[k][j][3] * v[k][j][3]);
;                 const float rstd = __builtin_amdgcn_rsqf(wave_sum(ss) * (1.0f / DM) + EPS);
;                 const float* shift = R.mod + ((size_t)(R.ln * 9 + bb) * NMOD + R.si) * DM; const float* scale = shift + DM;
;                 bf16* hr = R.H + (size_t)row * DM;
; #pragma unroll
;                 for (int j = 0; j < 4; ++j) { const f32x4 gp = *(const f32x4*)(R.gpre + lane * 4 + 256 * j), sh = *(const f32x4*)(shift + lane * 4 + 256 * j), sc = *(const f32x4*)(scale + lane * 4 + 256 * j);
;                     const f32x4 hv = (v[k][j] * rstd * gp) * (sc + 1.0f) + sh;
;                     u32x2 w; w.x = pk2(hv[0], hv[1]); w.y = pk2(hv[2], hv[3]); *(u32x2*)(hr + lane * 4 + 256 * j) = w; }
;             }
	v_pk_fma_f32 v[12:13], v[64:65], v[32:33], v[12:13]
	v_pk_fma_f32 v[14:15], v[66:67], v[34:35], v[14:15]
	global_store_dwordx4 v160, v[12:15], s[40:41] nt
	v_lshlrev_b32_e32 v32, 16, v52
	v_and_b32_e32 v33, 0xffff0000, v52
	v_lshlrev_b32_e32 v34, 16, v53
	v_and_b32_e32 v35, 0xffff0000, v53
	v_pk_mul_f32 v[32:33], v[32:33], v[164:165] op_sel_hi:[1,0]
	v_pk_mul_f32 v[34:35], v[34:35], v[164:165] op_sel_hi:[1,0]
	v_pk_mul_f32 v[32:33], v[222:223], v[32:33]
	v_pk_mul_f32 v[34:35], v[224:225], v[34:35]
	s_waitcnt vmcnt(23)
	v_pk_fma_f32 v[8:9], v[68:69], v[32:33], v[8:9]
	v_pk_fma_f32 v[10:11], v[70:71], v[34:35], v[10:11]
	global_store_dwordx4 v160, v[8:11], s[40:41] offset:1024 nt
	v_lshlrev_b32_e32 v32, 16, v50
	v_and_b32_e32 v33, 0xffff0000, v50
	v_lshlrev_b32_e32 v34, 16, v51
	v_and_b32_e32 v35, 0xffff0000, v51
	v_pk_mul_f32 v[32:33], v[32:33], v[164:165] op_sel_hi:[1,0]
	v_pk_mul_f32 v[34:35], v[34:35], v[164:165] op_sel_hi:[1,0]
	v_pk_mul_f32 v[32:33], v[226:227], v[32:33]
	v_pk_mul_f32 v[34:35], v[228:229], v[34:35]
	s_waitcnt vmcnt(23)
	v_pk_fma_f32 v[4:5], v[72:73], v[32:33], v[4:5]
	v_pk_fma_f32 v[6:7], v[74:75], v[34:35], v[6:7]
	global_store_dwordx4 v160, v[4:7], s[40:41] offset:2048 nt
	v_lshlrev_b32_e32 v32, 16, v48
	v_and_b32_e32 v33, 0xffff0000, v48
	v_lshlrev_b32_e32 v34, 16, v49
	v_and_b32_e32 v35, 0xffff0000, v49
	v_pk_mul_f32 v[32:33], v[32:33], v[164:165] op_sel_hi:[1,0]
	v_pk_mul_f32 v[34:35], v[34:35], v[164:165] op_sel_hi:[1,0]
	v_pk_mul_f32 v[32:33], v[230:231], v[32:33]
	v_pk_mul_f32 v[34:35], v[232:233], v[34:35]
	s_waitcnt vmcnt(23)
	v_pk_fma_f32 v[0:1], v[76:77], v[32:33], v[0:1]
	v_pk_fma_f32 v[2:3], v[78:79], v[34:35], v[2:3]
	global_store_dwordx4 v160, v[0:3], s[40:41] offset:3072 nt
	global_load_dwordx4 v[64:67], v160, s[50:51]
	global_load_dwordx4 v[68:71], v160, s[50:51] offset:1024
	global_load_dwordx4 v[72:75], v160, s[50:51] offset:2048
	global_load_dwordx4 v[76:79], v160, s[50:51] offset:3072
	v_add_co_u32_e32 v250, vcc, 0xfbc00000, v46
	v_addc_co_u32_e32 v251, vcc, -1, v47, vcc
	v_pk_mul_f32 v[166:167], v[12:13], v[12:13]
	v_pk_mul_f32 v[168:169], v[14:15], v[14:15]
	v_pk_fma_f32 v[166:167], v[8:9], v[8:9], v[166:167]
	v_pk_fma_f32 v[168:169], v[10:11], v[10:11], v[168:169]
	v_pk_fma_f32 v[166:167], v[4:5], v[4:5], v[166:167]
	v_pk_fma_f32 v[168:169], v[6:7], v[6:7], v[168:169]
	v_pk_fma_f32 v[166:167], v[0:1], v[0:1], v[166:167]
	v_pk_fma_f32 v[168:169], v[2:3], v[2:3], v[168:169]
	v_pk_add_f32 v[166:167], v[166:167], v[168:169]
	s_nop 0
	v_add_f32_e32 v164, v166, v167
	v_mov_b32_e32 v165, v164
	s_nop 1
	v_permlane32_swap_b32_e32 v165, v164
	v_add_f32_e32 v164, v164, v165
	v_mov_b32_e32 v165, v164
	s_nop 1
	v_permlane16_swap_b32_e32 v165, v164
	v_add_f32_e32 v164, v164, v165
	s_nop 1
	v_add_f32_dpp v164, v164, v164 row_ror:8 row_mask:0xf bank_mask:0xf
	s_nop 1
	v_add_f32_dpp v164, v164, v164 row_ror:4 row_mask:0xf bank_mask:0xf
	s_nop 1
	v_add_f32_dpp v164, v164, v164 row_ror:2 row_mask:0xf bank_mask:0xf
	s_nop 1
	v_add_f32_dpp v164, v164, v164 row_ror:1 row_mask:0xf bank_mask:0xf
	s_nop 0
	v_fmamk_f32 v164, v164, 0x3a800000, v200
	v_rsq_f32_e32 v164, v164
	s_nop 0
	v_pk_mul_f32 v[12:13], v[12:13], v[164:165] op_sel_hi:[1,0]
	v_pk_mul_f32 v[14:15], v[14:15], v[164:165] op_sel_hi:[1,0]
	v_pk_mul_f32 v[12:13], v[234:235], v[12:13]
	v_pk_mul_f32 v[14:15], v[236:237], v[14:15]
	s_waitcnt vmcnt(15)
	v_pk_add_f32 v[172:173], v[172:173], 1.0 op_sel_hi:[1,0]
	v_pk_add_f32 v[174:175], v[174:175], 1.0 op_sel_hi:[1,0]
	v_pk_fma_f32 v[12:13], v[172:173], v[12:13], v[80:81]
	v_pk_fma_f32 v[14:15], v[174:175], v[14:15], v[82:83]
	v_cvt_pk_bf16_f32 v12, v12, v13
	v_cvt_pk_bf16_f32 v13, v14, v15
	global_store_dwordx2 v[250:251], v[12:13], off offset:-1536
	global_load_dwordx4 v[80:83], v160, s[52:53]
	v_pk_mul_f32 v[8:9], v[8:9], v[164:165] op_sel_hi:[1,0]
	v_pk_mul_f32 v[10:11], v[10:11], v[164:165] op_sel_hi:[1,0]
	v_pk_mul_f32 v[8:9], v[238:239], v[8:9]
	v_pk_mul_f32 v[10:11], v[240:241], v[10:11]
	s_waitcnt vmcnt(16)
	v_pk_add_f32 v[176:177], v[176:177], 1.0 op_sel_hi:[1,0]
	v_pk_add_f32 v[178:179], v[178:179], 1.0 op_sel_hi:[1,0]
	v_pk_fma_f32 v[8:9], v[176:177], v[8:9], v[84:85]
	v_pk_fma_f32 v[10:11], v[178:179], v[10:11], v[86:87]
	v_cvt_pk_bf16_f32 v8, v8, v9
	v_cvt_pk_bf16_f32 v9, v10, v11
	global_store_dwordx2 v[250:251], v[8:9], off offset:-1024
	global_load_dwordx4 v[84:87], v160, s[52:53] offset:1024
	v_pk_mul_f32 v[4:5], v[4:5], v[164:165] op_sel_hi:[1,0]
	v_pk_mul_f32 v[6:7], v[6:7], v[164:165] op_sel_hi:[1,0]
	v_pk_mul_f32 v[4:5], v[242:243], v[4:5]
	v_pk_mul_f32 v[6:7], v[244:245], v[6:7]
	s_waitcnt vmcnt(17)
	v_pk_add_f32 v[180:181], v[180:181], 1.0 op_sel_hi:[1,0]
	v_pk_add_f32 v[182:183], v[182:183], 1.0 op_sel_hi:[1,0]
	v_pk_fma_f32 v[4:5], v[180:181], v[4:5], v[88:89]
	v_pk_fma_f32 v[6:7], v[182:183], v[6:7], v[90:91]
	v_cvt_pk_bf16_f32 v4, v4, v5
	v_cvt_pk_bf16_f32 v5, v6, v7
	global_store_dwordx2 v[250:251], v[4:5], off offset:-512
	global_load_dwordx4 v[88:91], v160, s[52:53] offset:2048
	v_pk_mul_f32 v[0:1], v[0:1], v[164:165] op_sel_hi:[1,0]
	v_pk_mul_f32 v[2:3], v[2:3], v[164:165] op_sel_hi:[1,0]
	v_pk_mul_f32 v[0:1], v[246:247], v[0:1]
	v_pk_mul_f32 v[2:3], v[248:249], v[2:3]
	s_waitcnt vmcnt(18)
	v_pk_add_f32 v[184:185], v[184:185], 1.0 op_sel_hi:[1,0]
	v_pk_add_f32 v[186:187], v[186:187], 1.0 op_sel_hi:[1,0]
	v_pk_fma_f32 v[0:1], v[184:185], v[0:1], v[92:93]
	v_pk_fma_f32 v[2:3], v[186:187], v[2:3], v[94:95]
	v_cvt_pk_bf16_f32 v0, v0, v1
	v_cvt_pk_bf16_f32 v1, v2, v3
	global_store_dwordx2 v[250:251], v[0:1], off
	global_load_dwordx4 v[92:95], v160, s[52:53] offset:3072
	s_waitcnt vmcnt(28)
; __device__ __forceinline__ float bflo(unsigned w) { return __uint_as_float(w << 16); }
; __device__ __forceinline__ float bfhi(unsigned w) { return __uint_as_float(w & 0xffff0000u); }
;     __device__ __forceinline__ void init(int N, int G, int c, int latent_only) { lat = latent_only; b.init(latent_only ? NB * SEQ : M, N, G, c); }
;     __device__ __forceinline__ void init(int c_, unsigned* cnt_) { lat.init(NB * SEQ, FF2, 1, 0); c = c_; cnt = cnt_; }
; __device__ __forceinline__ void row_pass(const RowPass& R, int gw, int ngw, int lane) {
;     ...
;             if (R.update) {
;                 f32x4 y[4]; float ss = 0.f;
; #pragma unroll
;                 for (int j = 0; j < 4; ++j) { const u32x2 w = yw[k][j]; y[j] = (f32x4){bflo(w.x), bfhi(w.x), bflo(w.y), bfhi(w.y)};
;                     ss += (y[j][0] * y[j][0] + y[j][1] * y[j][1]) + (y[j][2] * y[j][2] + y[j][3] * y[j][3]); }
;                 const float rstd = __builtin_amdgcn_rsqf(wave_sum(ss) * (1.0f / DM) + EPS);
;                 const float* gate = R.mod + ((size_t)(R.lg * 9 + bb) * NMOD + R.gi) * DM;
; #pragma unroll
;                 for (int j = 0; j < 4; ++j) { const f32x4 g = *(const f32x4*)(gate + lane * 4 + 256 * j), gp = *(const f32x4*)(R.gpost + lane * 4 + 256 * j);
;                     v[k][j] = v[k][j] + g * (y[j] * rstd * gp); }
;             }
;             if (R.init || R.update) {
; #pragma unroll
;                 for (int j = 0; j < 4; ++j) __builtin_nontemporal_store(v[k][j], (f32x4*)(xrow[k] + lane * 4 + 256 * j));
	v_lshlrev_b32_e32 v32, 16, v62
	v_and_b32_e32 v33, 0xffff0000, v62
	v_lshlrev_b32_e32 v34, 16, v63
	v_and_b32_e32 v35, 0xffff0000, v63
	v_pk_mul_f32 v[166:167], v[32:33], v[32:33]
	v_pk_mul_f32 v[168:169], v[34:35], v[34:35]
	v_lshlrev_b32_e32 v32, 16, v60
	v_and_b32_e32 v33, 0xffff0000, v60
	v_lshlrev_b32_e32 v34, 16, v61
	v_and_b32_e32 v35, 0xffff0000, v61
	v_pk_fma_f32 v[166:167], v[32:33], v[32:33], v[166:167]
	v_pk_fma_f32 v[168:169], v[34:35], v[34:35], v[168:169]
	v_lshlrev_b32_e32 v32, 16, v58
	v_and_b32_e32 v33, 0xffff0000, v58
	v_lshlrev_b32_e32 v34, 16, v59
	v_and_b32_e32 v35, 0xffff0000, v59
	v_pk_fma_f32 v[166:167], v[32:33], v[32:33], v[166:167]
	v_pk_fma_f32 v[168:169], v[34:35], v[34:35], v[168:169]
	v_lshlrev_b32_e32 v32, 16, v56
	v_and_b32_e32 v33, 0xffff0000, v56
	v_lshlrev_b32_e32 v34, 16, v57
	v_and_b32_e32 v35, 0xffff0000, v57
	v_pk_fma_f32 v[166:167], v[32:33], v[32:33], v[166:167]
	v_pk_fma_f32 v[168:169], v[34:35], v[34:35], v[168:169]
	v_pk_add_f32 v[166:167], v[166:167], v[168:169]
	s_nop 0
	v_add_f32_e32 v164, v166, v167
	v_mov_b32_e32 v165, v164
	s_nop 1
	v_permlane32_swap_b32_e32 v165, v164
	v_add_f32_e32 v164, v164, v165
	v_mov_b32_e32 v165, v164
	s_nop 1
	v_permlane16_swap_b32_e32 v165, v164
	v_add_f32_e32 v164, v164, v165
	s_nop 1
	v_add_f32_dpp v164, v164, v164 row_ror:8 row_mask:0xf bank_mask:0xf
	s_nop 1
	v_add_f32_dpp v164, v164, v164 row_ror:4 row_mask:0xf bank_mask:0xf
	s_nop 1
	v_add_f32_dpp v164, v164, v164 row_ror:2 row_mask:0xf bank_mask:0xf
	s_nop 1
	v_add_f32_dpp v164, v164, v164 row_ror:1 row_mask:0xf bank_mask:0xf
	s_nop 0
	v_fmamk_f32 v164, v164, 0x3a800000, v200
	v_rsq_f32_e32 v164, v164
	v_lshlrev_b32_e32 v32, 16, v62
	v_and_b32_e32 v33, 0xffff0000, v62
	v_lshlrev_b32_e32 v34, 16, v63
	v_and_b32_e32 v35, 0xffff0000, v63
	v_pk_mul_f32 v[32:33], v[32:33], v[164:165] op_sel_hi:[1,0]
	v_pk_mul_f32 v[34:35], v[34:35], v[164:165] op_sel_hi:[1,0]
	v_pk_mul_f32 v[32:33], v[218:219], v[32:33]
	v_pk_mul_f32 v[34:35], v[220:221], v[34:35]
	s_waitcnt vmcnt(19)
	v_pk_fma_f32 v[16:17], v[188:189], v[32:33], v[16:17]
	v_pk_fma_f32 v[18:19], v[190:191], v[34:35], v[18:19]
	global_store_dwordx4 v160, v[16:19], s[64:65] nt
	v_lshlrev_b32_e32 v32, 16, v60
	v_and_b32_e32 v33, 0xffff0000, v60
	v_lshlrev_b32_e32 v34, 16, v61
	v_and_b32_e32 v35, 0xffff0000, v61
	v_pk_mul_f32 v[32:33], v[32:33], v[164:165] op_sel_hi:[1,0]
	v_pk_mul_f32 v[34:35], v[34:35], v[164:165] op_sel_hi:[1,0]
	v_pk_mul_f32 v[32:33], v[222:223], v[32:33]
	v_pk_mul_f32 v[34:35], v[224:225], v[34:35]
	s_waitcnt vmcnt(19)
	v_pk_fma_f32 v[20:21], v[192:193], v[32:33], v[20:21]
	v_pk_fma_f32 v[22:23], v[194:195], v[34:35], v[22:23]
	global_store_dwordx4 v160, v[20:23], s[64:65] offset:1024 nt
	v_lshlrev_b32_e32 v32, 16, v58
	v_and_b32_e32 v33, 0xffff0000, v58
	v_lshlrev_b32_e32 v34, 16, v59
	v_and_b32_e32 v35, 0xffff0000, v59
	v_pk_mul_f32 v[32:33], v[32:33], v[164:165] op_sel_hi:[1,0]
	v_pk_mul_f32 v[34:35], v[34:35], v[164:165] op_sel_hi:[1,0]
	v_pk_mul_f32 v[32:33], v[226:227], v[32:33]
	v_pk_mul_f32 v[34:35], v[228:229], v[34:35]
	s_waitcnt vmcnt(19)
	v_pk_fma_f32 v[24:25], v[196:197], v[32:33], v[24:25]
	v_pk_fma_f32 v[26:27], v[198:199], v[34:35], v[26:27]
	global_store_dwordx4 v160, v[24:27], s[64:65] offset:2048 nt
	v_lshlrev_b32_e32 v32, 16, v56
	v_and_b32_e32 v33, 0xffff0000, v56
	v_lshlrev_b32_e32 v34, 16, v57
	v_and_b32_e32 v35, 0xffff0000, v57
	v_pk_mul_f32 v[32:33], v[32:33], v[164:165] op_sel_hi:[1,0]
	v_pk_mul_f32 v[34:35], v[34:35], v[164:165] op_sel_hi:[1,0]
	v_pk_mul_f32 v[32:33], v[230:231], v[32:33]
	v_pk_mul_f32 v[34:35], v[232:233], v[34:35]
	s_waitcnt vmcnt(19)
; __device__ __forceinline__ unsigned pk2(float lo, float hi) { return pg8::cvt_pk_bf16(lo, hi); }
;     __device__ __forceinline__ void init(int N, int G, int c, int latent_only) { lat = latent_only; b.init(latent_only ? NB * SEQ : M, N, G, c); }
;     __device__ __forceinline__ void init(int c_, unsigned* cnt_) { lat.init(NB * SEQ, FF2, 1, 0); c = c_; cnt = cnt_; }
; __device__ __forceinline__ void row_pass(const RowPass& R, int gw, int ngw, int lane) {
;     ...
;             if (R.init || R.update) {
; #pragma unroll
;                 for (int j = 0; j < 4; ++j) __builtin_nontemporal_store(v[k][j], (f32x4*)(xrow[k] + lane * 4 + 256 * j));
;             }
;             if (R.norm_out) {
;                 float ss = 0.f;
; #pragma unroll
;                 for (int j = 0; j < 4; ++j) ss += (v[k][j][0] * v[k][j][0] + v[k][j][1] * v[k][j][1]) + (v[k][j][2] * v[k][j][2] + v[k][j][3] * v[k][j][3]);
;                 const float rstd = __builtin_amdgcn_rsqf(wave_sum(ss) * (1.0f / DM) + EPS);
;                 const float* shift = R.mod + ((size_t)(R.ln * 9 + bb) * NMOD + R.si) * DM; const float* scale = shift + DM;
;                 bf16* hr = R.H + (size_t)row * DM;
; #pragma unroll
;                 for (int j = 0; j < 4; ++j) { const f32x4 gp = *(const f32x4*)(R.gpre + lane * 4 + 256 * j), sh = *(const f32x4*)(shift + lane * 4 + 256 * j), sc = *(const f32x4*)(scale + lane * 4 + 256 * j);
;                     const f32x4 hv = (v[k][j] * rstd * gp) * (sc + 1.0f) + sh;
;                     u32x2 w; w.x = pk2(hv[0], hv[1]); w.y = pk2(hv[2], hv[3]); *(u32x2*)(hr + lane * 4 + 256 * j) = w; }
;             }
	v_pk_fma_f32 v[28:29], v[96:97], v[32:33], v[28:29]
	v_pk_fma_f32 v[30:31], v[98:99], v[34:35], v[30:31]
	global_store_dwordx4 v160, v[28:31], s[64:65] offset:3072 nt
	v_pk_mul_f32 v[166:167], v[16:17], v[16:17]
	v_pk_mul_f32 v[168:169], v[18:19], v[18:19]
	v_pk_fma_f32 v[166:167], v[20:21], v[20:21], v[166:167]
	v_pk_fma_f32 v[168:169], v[22:23], v[22:23], v[168:169]
	v_pk_fma_f32 v[166:167], v[24:25], v[24:25], v[166:167]
	v_pk_fma_f32 v[168:169], v[26:27], v[26:27], v[168:169]
	v_pk_fma_f32 v[166:167], v[28:29], v[28:29], v[166:167]
	v_pk_fma_f32 v[168:169], v[30:31], v[30:31], v[168:169]
	v_pk_add_f32 v[166:167], v[166:167], v[168:169]
	s_nop 0
	v_add_f32_e32 v164, v166, v167
	v_mov_b32_e32 v165, v164
	s_nop 1
	v_permlane32_swap_b32_e32 v165, v164
	v_add_f32_e32 v164, v164, v165
	v_mov_b32_e32 v165, v164
	s_nop 1
	v_permlane16_swap_b32_e32 v165, v164
	v_add_f32_e32 v164, v164, v165
	s_nop 1
	v_add_f32_dpp v164, v164, v164 row_ror:8 row_mask:0xf bank_mask:0xf
	s_nop 1
	v_add_f32_dpp v164, v164, v164 row_ror:4 row_mask:0xf bank_mask:0xf
	s_nop 1
	v_add_f32_dpp v164, v164, v164 row_ror:2 row_mask:0xf bank_mask:0xf
	s_nop 1
	v_add_f32_dpp v164, v164, v164 row_ror:1 row_mask:0xf bank_mask:0xf
	s_nop 0
	v_fmamk_f32 v164, v164, 0x3a800000, v200
	v_rsq_f32_e32 v164, v164
	s_nop 0
	v_pk_mul_f32 v[16:17], v[16:17], v[164:165] op_sel_hi:[1,0]
	v_pk_mul_f32 v[18:19], v[18:19], v[164:165] op_sel_hi:[1,0]
	v_pk_mul_f32 v[16:17], v[234:235], v[16:17]
	v_pk_mul_f32 v[18:19], v[236:237], v[18:19]
	s_waitcnt vmcnt(10)
	v_pk_add_f32 v[80:81], v[80:81], 1.0 op_sel_hi:[1,0]
	v_pk_add_f32 v[82:83], v[82:83], 1.0 op_sel_hi:[1,0]
	v_pk_fma_f32 v[16:17], v[80:81], v[16:17], v[64:65]
	v_pk_fma_f32 v[18:19], v[82:83], v[18:19], v[66:67]
	v_cvt_pk_bf16_f32 v16, v16, v17
	v_cvt_pk_bf16_f32 v17, v18, v19
	global_store_dwordx2 v[252:253], v[16:17], off
	v_pk_mul_f32 v[20:21], v[20:21], v[164:165] op_sel_hi:[1,0]
	v_pk_mul_f32 v[22:23], v[22:23], v[164:165] op_sel_hi:[1,0]
	v_pk_mul_f32 v[20:21], v[238:239], v[20:21]
	v_pk_mul_f32 v[22:23], v[240:241], v[22:23]
	s_waitcnt vmcnt(9)
	v_pk_add_f32 v[84:85], v[84:85], 1.0 op_sel_hi:[1,0]
	v_pk_add_f32 v[86:87], v[86:87], 1.0 op_sel_hi:[1,0]
	v_pk_fma_f32 v[20:21], v[84:85], v[20:21], v[68:69]
	v_pk_fma_f32 v[22:23], v[86:87], v[22:23], v[70:71]
	v_cvt_pk_bf16_f32 v20, v20, v21
	v_cvt_pk_bf16_f32 v21, v22, v23
	global_store_dwordx2 v[252:253], v[20:21], off offset:512
	v_pk_mul_f32 v[24:25], v[24:25], v[164:165] op_sel_hi:[1,0]
	v_pk_mul_f32 v[26:27], v[26:27], v[164:165] op_sel_hi:[1,0]
	v_pk_mul_f32 v[24:25], v[242:243], v[24:25]
	v_pk_mul_f32 v[26:27], v[244:245], v[26:27]
	s_waitcnt vmcnt(8)
	v_pk_add_f32 v[88:89], v[88:89], 1.0 op_sel_hi:[1,0]
	v_pk_add_f32 v[90:91], v[90:91], 1.0 op_sel_hi:[1,0]
	v_pk_fma_f32 v[24:25], v[88:89], v[24:25], v[72:73]
	v_pk_fma_f32 v[26:27], v[90:91], v[26:27], v[74:75]
	v_cvt_pk_bf16_f32 v24, v24, v25
	v_cvt_pk_bf16_f32 v25, v26, v27
	global_store_dwordx2 v[252:253], v[24:25], off offset:1024
	v_pk_mul_f32 v[28:29], v[28:29], v[164:165] op_sel_hi:[1,0]
	v_pk_mul_f32 v[30:31], v[30:31], v[164:165] op_sel_hi:[1,0]
	v_pk_mul_f32 v[28:29], v[246:247], v[28:29]
	v_pk_mul_f32 v[30:31], v[248:249], v[30:31]
	s_waitcnt vmcnt(7)
	v_pk_add_f32 v[92:93], v[92:93], 1.0 op_sel_hi:[1,0]
	v_pk_add_f32 v[94:95], v[94:95], 1.0 op_sel_hi:[1,0]
	v_pk_fma_f32 v[28:29], v[92:93], v[28:29], v[76:77]
	v_pk_fma_f32 v[30:31], v[94:95], v[30:31], v[78:79]
	v_cvt_pk_bf16_f32 v28, v28, v29
	v_cvt_pk_bf16_f32 v29, v30, v31
	global_store_dwordx2 v[252:253], v[28:29], off offset:1536
	s_branch .LBB0_131

;     __device__ __forceinline__ void init(int N, int G, int c, int latent_only) { lat = latent_only; b.init(latent_only ? NB * SEQ : M, N, G, c); }
;     __device__ __forceinline__ void init(int c_, unsigned* cnt_) { lat.init(NB * SEQ, FF2, 1, 0); c = c_; cnt = cnt_; }
; __device__ __forceinline__ void row_pass(const RowPass& R, int gw, int ngw, int lane) {
;     constexpr int NR = 2;
;     for (int row0 = gw; row0 < M; row0 += NR * ngw) {
;         f32x4 v[NR][4]; u32x2 yw[NR][4]; bool act[NR]; float* xrow[NR]; int bbs[NR];
; #pragma unroll
;         for (int k = 0; k < NR; ++k) {
;             const int row = row0 + k * ngw;
;             const int rowc = row < M ? row : row0;
;             const int b = rowc / RPB, i = rowc - b * RPB; const bool isctx = i < CTXL;
;             act[k] = (row < M) && !(isctx && R.skip_ctx);
;             bbs[k] = isctx ? 8 : b;
;             xrow[k] = isctx ? R.xc + ((size_t)b * CTXL + i) * DM : R.out + ((size_t)b * SEQ + (i - CTXL)) * DM;
;             const float* src = R.init ? (isctx ? R.ctx_in + ((size_t)b * CTXL + i) * DM : R.x_in + ((size_t)b * SEQ + (i - CTXL)) * DM) : xrow[k];
;             if (act[k]) {
; #pragma unroll
;                 for (int j = 0; j < 4; ++j) v[k][j] = __builtin_nontemporal_load((const f32x4*)(src + lane * 4 + 256 * j));
; __global__ void __launch_bounds__(NTHR, 2) fwd_kernel(Args A_) {
;     ...
;             } else {
;                 const int last = (l == DEPTH - 1);
;                 RowPass R{A->x, A->ctx, A->out, xc, Yb, Hb, modp, A->g_post_ffn + l * DM, A->g_pre_mix + (last ? l : l + 1) * DM, 0, 1, last ? 0 : 1, l, 5, last ? l : l + 1, 0, last};
;                 row_pass(R, gw, ngw, lane);
.LBB0_145:
	v_readlane_b32 s6, v255, 17
	v_readlane_b32 s7, v255, 18
	s_and_b64 vcc, exec, s[6:7]
	s_cbranch_vccz .LBB0_160
	s_cmp_gt_i32 s36, 0x87ff
	s_cbranch_scc1 .LBB0_159
	s_sub_i32 s3, s57, 30
	s_cmp_lt_u32 s3, -7
	s_cselect_b64 s[4:5], -1, 0
	s_cmp_lg_u64 s[4:5], 0
	s_load_dwordx2 s[8:9], s[0:1], 0x30
	s_addc_u32 s13, s12, 0
	s_lshl_b32 s6, s13, 10
	s_ashr_i32 s7, s6, 31
	s_lshl_b64 s[6:7], s[6:7], 2
	s_load_dwordx2 s[22:23], s[0:1], 0xa0
	s_load_dwordx2 s[10:11], s[0:1], 0x48
	s_waitcnt lgkmcnt(0)
	s_add_u32 s6, s8, s6
	s_addc_u32 s7, s9, s7
	s_lshl_b32 s8, s12, 10
	s_ashr_i32 s9, s8, 31
	s_lshl_b64 s[8:9], s[8:9], 2
	s_add_u32 s8, s10, s8
	s_addc_u32 s9, s11, s9
	s_waitcnt vmcnt(0)
	v_lshlrev_b32_e32 v0, 4, v216
	v_mov_b32_e32 v1, v161
	s_ashr_i32 s37, s36, 31
	v_lshl_add_u64 v[44:45], s[6:7], 0, v[0:1]
	s_lshl_b64 s[6:7], s[36:37], 11
	s_add_u32 s6, s28, s6
	v_lshlrev_b32_e32 v160, 3, v216
	s_addc_u32 s7, s29, s7
	v_lshl_add_u64 v[42:43], s[8:9], 0, v[0:1]
	v_lshl_add_u64 v[0:1], s[6:7], 0, v[160:161]
	s_mov_b64 s[6:7], 0xa7fa600
	v_lshlrev_b32_e32 v36, 2, v216
	v_lshl_add_u64 v[38:39], s[20:21], 0, v[160:161]
	v_lshl_add_u64 v[40:41], s[60:61], 0, v[160:161]
	s_mul_i32 s3, s12, 9
	s_mul_i32 s13, s13, 9
	v_lshl_add_u64 v[46:47], v[0:1], 0, s[6:7]
	global_load_dwordx4 v[218:221], v[42:43], off
	global_load_dwordx4 v[222:225], v[42:43], off offset:1024
	global_load_dwordx4 v[226:229], v[42:43], off offset:2048
	global_load_dwordx4 v[230:233], v[42:43], off offset:3072
	global_load_dwordx4 v[234:237], v[44:45], off
	global_load_dwordx4 v[238:241], v[44:45], off offset:1024
	global_load_dwordx4 v[242:245], v[44:45], off offset:2048
	global_load_dwordx4 v[246:249], v[44:45], off offset:3072
	s_mov_b32 s19, s36
	s_branch .LBB0_149

; __device__ __forceinline__ void row_pass(const RowPass& R, int gw, int ngw, int lane) {
;     ...
;     for (int row0 = gw; row0 < M; row0 += NR * ngw) {
;         f32x4 v[NR][4]; u32x2 yw[NR][4]; bool act[NR]; float* xrow[NR]; int bbs[NR];
; #pragma unroll
;         for (int k = 0; k < NR; ++k) {
;             const int row = row0 + k * ngw;
;             const int rowc = row < M ? row : row0;
;             const int b = rowc / RPB, i = rowc - b * RPB; const bool isctx = i < CTXL;
;             act[k] = (row < M) && !(isctx && R.skip_ctx);
;             bbs[k] = isctx ? 8 : b;
;             xrow[k] = isctx ? R.xc + ((size_t)b * CTXL + i) * DM : R.out + ((size_t)b * SEQ + (i - CTXL)) * DM;
;             const float* src = R.init ? (isctx ? R.ctx_in + ((size_t)b * CTXL + i) * DM : R.x_in + ((size_t)b * SEQ + (i - CTXL)) * DM) : xrow[k];
;             if (act[k]) {
; #pragma unroll
;                 for (int j = 0; j < 4; ++j) v[k][j] = __builtin_nontemporal_load((const f32x4*)(src + lane * 4 + 256 * j));
;                 if (R.update) { const bf16* yr = R.Y + (size_t)rowc * DM;
; #pragma unroll
;                     for (int j = 0; j < 4; ++j) yw[k][j] = __builtin_nontemporal_load((const u32x2*)(yr + lane * 4 + 256 * j)); }
;             }
;         }
; #pragma unroll
;         for (int k = 0; k < NR; ++k) {
;             if (!act[k]) continue;
;             const int row = row0 + k * ngw, bb = bbs[k];
;             if (R.update) {
;                 f32x4 y[4]; float ss = 0.f;
; #pragma unroll
;                 for (int j = 0; j < 4; ++j) { const u32x2 w = yw[k][j]; y[j] = (f32x4){bflo(w.x), bfhi(w.x), bflo(w.y), bfhi(w.y)};
;                     ss += (y[j][0] * y[j][0] + y[j][1] * y[j][1]) + (y[j][2] * y[j][2] + y[j][3] * y[j][3]); }
;                 const float rstd = __builtin_amdgcn_rsqf(wave_sum(ss) * (1.0f / DM) + EPS);
;                 const float* gate = R.mod + ((size_t)(R.lg * 9 + bb) * NMOD + R.gi) * DM;
; #pragma unroll
;                 for (int j = 0; j < 4; ++j) { const f32x4 g = *(const f32x4*)(gate + lane * 4 + 256 * j), gp = *(const f32x4*)(R.gpost + lane * 4 + 256 * j);
;                     v[k][j] = v[k][j] + g * (y[j] * rstd * gp); }
; __global__ void __launch_bounds__(NTHR, 2) fwd_kernel(Args A_) {
;     ...
;             } else {
;                 const int last = (l == DEPTH - 1);
.LBB0_149:
	s_mul_hi_i32 s6, s19, 0x78787879
	s_lshr_b32 s7, s6, 31
	s_ashr_i32 s6, s6, 11
	s_add_i32 s6, s6, s7
	s_mul_i32 s7, s6, 0xffffef00
	s_add_i32 s7, s19, s7
	s_cmpk_gt_i32 s7, 0xff
	s_cselect_b64 s[50:51], -1, 0
	s_add_i32 s8, s44, s19
	s_cmp_lt_i32 s8, 0x8800
	s_cbranch_scc0 .Lr3_slow
	s_mul_hi_i32 s9, s8, 0x78787879
	s_lshr_b32 s25, s9, 31
	s_ashr_i32 s9, s9, 11
	s_add_i32 s9, s9, s25
	s_mul_i32 s25, s9, 0xffffef00
	s_add_i32 s25, s8, s25
	s_cmpk_gt_i32 s25, 0xff
	s_cselect_b64 s[52:53], -1, 0
	s_cmp_lg_u64 s[4:5], 0
	s_cbranch_scc0 .Lr3_slow
	v_lshlrev_b32_e32 v160, 2, v36
	s_add_i32 s72, s7, 0xffffff00
	s_cmp_lg_u64 s[50:51], 0
	s_cselect_b32 s27, s22, s49
	s_cselect_b32 s32, s23, s55
	s_cselect_b32 s37, 24, 20
	s_cselect_b32 s72, s72, s7
	s_cselect_b32 s85, s6, 8
	s_mov_b32 s40, s6
	s_mov_b32 s41, 0
	s_lshl_b64 s[40:41], s[40:41], s37
	s_add_u32 s40, s27, s40
	s_addc_u32 s41, s32, s41
	s_lshl_b32 s72, s72, 12
	s_add_u32 s40, s40, s72
	s_addc_u32 s41, s41, 0
	s_add_i32 s27, s85, s3
	s_mul_hi_i32 s32, s27, 0x6000
	s_mulk_i32 s27, 0x6000
	s_add_u32 s66, s34, s27
	s_addc_u32 s67, s35, s32
	s_add_u32 s66, s66, 0x5000
	s_addc_u32 s67, s67, 0
	s_add_i32 s27, s85, s13
	s_mul_hi_i32 s32, s27, 0x6000
	s_mulk_i32 s27, 0x6000
	s_add_u32 s38, s34, s27
	s_addc_u32 s39, s35, s32
	s_add_u32 s46, s38, 0x1000
	s_addc_u32 s47, s39, 0
	global_load_dwordx4 v[12:15], v160, s[40:41] nt
	global_load_dwordx4 v[8:11], v160, s[40:41] offset:1024 nt
	global_load_dwordx4 v[4:7], v160, s[40:41] offset:2048 nt
	global_load_dwordx4 v[0:3], v160, s[40:41] offset:3072 nt
	global_load_dwordx2 v[54:55], v[46:47], off offset:-1536 nt
	global_load_dwordx2 v[52:53], v[46:47], off offset:-1024 nt
	global_load_dwordx2 v[50:51], v[46:47], off offset:-512 nt
	global_load_dwordx2 v[48:49], v[46:47], off nt
	global_load_dwordx4 v[64:67], v160, s[66:67]
	global_load_dwordx4 v[68:71], v160, s[66:67] offset:1024
	global_load_dwordx4 v[72:75], v160, s[66:67] offset:2048
	global_load_dwordx4 v[76:79], v160, s[66:67] offset:3072
	s_mov_b32 s6, s8
	s_ashr_i32 s7, s8, 31
	s_lshl_b64 s[6:7], s[6:7], 11
	v_lshl_add_u64 v[250:251], v[38:39], 0, s[6:7]
	v_lshl_add_u64 v[252:253], v[40:41], 0, s[6:7]
	s_mov_b64 s[6:7], s[52:53]
	s_add_i32 s72, s25, 0xffffff00
	s_cmp_lg_u64 s[6:7], 0
	s_cselect_b32 s27, s22, s49
	s_cselect_b32 s32, s23, s55
	s_cselect_b32 s37, 24, 20
	s_cselect_b32 s72, s72, s25
	s_cselect_b32 s85, s9, 8
	s_mov_b32 s64, s9
	s_mov_b32 s65, 0
	s_lshl_b64 s[64:65], s[64:65], s37
	s_add_u32 s64, s27, s64
	s_addc_u32 s65, s32, s65
	s_lshl_b32 s72, s72, 12
	s_add_u32 s64, s64, s72
	s_addc_u32 s65, s65, 0
	s_add_i32 s27, s85, s3
	s_mul_hi_i32 s32, s27, 0x6000
	s_mulk_i32 s27, 0x6000
	s_add_u32 s10, s34, s27
	s_addc_u32 s11, s35, s32
	s_add_u32 s10, s10, 0x5000
	s_addc_u32 s11, s11, 0
	s_add_i32 s27, s85, s13
	s_mul_hi_i32 s32, s27, 0x6000
	s_mulk_i32 s27, 0x6000
	s_add_u32 s50, s34, s27
	s_addc_u32 s51, s35, s32
	s_add_u32 s52, s50, 0x1000
	s_addc_u32 s53, s51, 0
	global_load_dwordx4 v[16:19], v160, s[64:65] nt
	global_load_dwordx4 v[20:23], v160, s[64:65] offset:1024 nt
	global_load_dwordx4 v[24:27], v160, s[64:65] offset:2048 nt
	global_load_dwordx4 v[28:31], v160, s[64:65] offset:3072 nt
	global_load_dwordx2 v[62:63], v[250:251], off nt
	global_load_dwordx2 v[60:61], v[250:251], off offset:512 nt
	global_load_dwordx2 v[58:59], v[250:251], off offset:1024 nt
	global_load_dwordx2 v[56:57], v[250:251], off offset:1536 nt
	global_load_dwordx4 v[80:83], v160, s[38:39]
	global_load_dwordx4 v[84:87], v160, s[38:39] offset:1024
	global_load_dwordx4 v[88:91], v160, s[38:39] offset:2048
	global_load_dwordx4 v[92:95], v160, s[38:39] offset:3072
	global_load_dwordx4 v[172:175], v160, s[46:47]
	global_load_dwordx4 v[176:179], v160, s[46:47] offset:1024
	global_load_dwordx4 v[180:183], v160, s[46:47] offset:2048
	global_load_dwordx4 v[184:187], v160, s[46:47] offset:3072
	global_load_dwordx4 v[188:191], v160, s[10:11]
	global_load_dwordx4 v[192:195], v160, s[10:11] offset:1024
	global_load_dwordx4 v[196:199], v160, s[10:11] offset:2048
	global_load_dwordx4 v[96:99], v160, s[10:11] offset:3072
	s_waitcnt vmcnt(24)
	v_lshlrev_b32_e32 v32, 16, v54
	v_and_b32_e32 v33, 0xffff0000, v54
	v_lshlrev_b32_e32 v34, 16, v55
	v_and_b32_e32 v35, 0xffff0000, v55
	v_pk_mul_f32 v[166:167], v[32:33], v[32:33]
	v_pk_mul_f32 v[168:169], v[34:35], v[34:35]
	v_lshlrev_b32_e32 v32, 16, v52
	v_and_b32_e32 v33, 0xffff0000, v52
	v_lshlrev_b32_e32 v34, 16, v53
	v_and_b32_e32 v35, 0xffff0000, v53
	v_pk_fma_f32 v[166:167], v[32:33], v[32:33], v[166:167]
	v_pk_fma_f32 v[168:169], v[34:35], v[34:35], v[168:169]
	v_lshlrev_b32_e32 v32, 16, v50
	v_and_b32_e32 v33, 0xffff0000, v50
	v_lshlrev_b32_e32 v34, 16, v51
	v_and_b32_e32 v35, 0xffff0000, v51
	v_pk_fma_f32 v[166:167], v[32:33], v[32:33], v[166:167]
	v_pk_fma_f32 v[168:169], v[34:35], v[34:35], v[168:169]
	v_lshlrev_b32_e32 v32, 16, v48
	v_and_b32_e32 v33, 0xffff0000, v48
	v_lshlrev_b32_e32 v34, 16, v49
	v_and_b32_e32 v35, 0xffff0000, v49
	v_pk_fma_f32 v[166:167], v[32:33], v[32:33], v[166:167]
	v_pk_fma_f32 v[168:169], v[34:35], v[34:35], v[168:169]
	v_pk_add_f32 v[166:167], v[166:167], v[168:169]
	s_nop 0
	v_add_f32_e32 v164, v166, v167
	v_mov_b32_e32 v165, v164
	s_nop 1
	v_permlane32_swap_b32_e32 v165, v164
	v_add_f32_e32 v164, v164, v165
	v_mov_b32_e32 v165, v164
	s_nop 1
	v_permlane16_swap_b32_e32 v165, v164
	v_add_f32_e32 v164, v164, v165
	s_nop 1
	v_add_f32_dpp v164, v164, v164 row_ror:8 row_mask:0xf bank_mask:0xf
	s_nop 1
	v_add_f32_dpp v164, v164, v164 row_ror:4 row_mask:0xf bank_mask:0xf
	s_nop 1
	v_add_f32_dpp v164, v164, v164 row_ror:2 row_mask:0xf bank_mask:0xf
	s_nop 1
	v_add_f32_dpp v164, v164, v164 row_ror:1 row_mask:0xf bank_mask:0xf
	s_nop 0
	v_fmamk_f32 v164, v164, 0x3a800000, v200
	v_rsq_f32_e32 v164, v164
	v_lshlrev_b32_e32 v32, 16, v54
	v_and_b32_e32 v33, 0xffff0000, v54
	v_lshlrev_b32_e32 v34, 16, v55
	v_and_b32_e32 v35, 0xffff0000, v55
	v_pk_mul_f32 v[32:33], v[32:33], v[164:165] op_sel_hi:[1,0]
	v_pk_mul_f32 v[34:35], v[34:35], v[164:165] op_sel_hi:[1,0]
	v_pk_mul_f32 v[32:33], v[218:219], v[32:33]
	v_pk_mul_f32 v[34:35], v[220:221], v[34:35]
	s_waitcnt vmcnt(23)
; __device__ __forceinline__ unsigned pk2(float lo, float hi) { return pg8::cvt_pk_bf16(lo, hi); }
;     __device__ __forceinline__ void init(int N, int G, int c, int latent_only) { lat = latent_only; b.init(latent_only ? NB * SEQ : M, N, G, c); }
;     __device__ __forceinline__ void init(int c_, unsigned* cnt_) { lat.init(NB * SEQ, FF2, 1, 0); c = c_; cnt = cnt_; }
; __device__ __forceinline__ void row_pass(const RowPass& R, int gw, int ngw, int lane) {
;     ...
;                 for (int j = 0; j < 4; ++j) { const f32x4 g = *(const f32x4*)(gate + lane * 4 + 256 * j), gp = *(const f32x4*)(R.gpost + lane * 4 + 256 * j);
;                     v[k][j] = v[k][j] + g * (y[j] * rstd * gp); }
;             }
;             if (R.init || R.update) {
; #pragma unroll
;                 for (int j = 0; j < 4; ++j) __builtin_nontemporal_store(v[k][j], (f32x4*)(xrow[k] + lane * 4 + 256 * j));
;             }
;             if (R.norm_out) {
;                 float ss = 0.f;
; #pragma unroll
;                 for (int j = 0; j < 4; ++j) ss += (v[k][j][0] * v[k][j][0] + v[k][j][1] * v[k][j][1]) + (v[k][j][2] * v[k][j][2] + v[k][j][3] * v[k][j][3]);
;                 const float rstd = __builtin_amdgcn_rsqf(wave_sum(ss) * (1.0f / DM) + EPS);
;                 const float* shift = R.mod + ((size_t)(R.ln * 9 + bb) * NMOD + R.si) * DM; const float* scale = shift + DM;
;                 bf16* hr = R.H + (size_t)row * DM;
; #pragma unroll
;                 for (int j = 0; j < 4; ++j) { const f32x4 gp = *(const f32x4*)(R.gpre + lane * 4 + 256 * j), sh = *(const f32x4*)(shift + lane * 4 + 256 * j), sc = *(const f32x4*)(scale + lane * 4 + 256 * j);
;                     const f32x4 hv = (v[k][j] * rstd * gp) * (sc + 1.0f) + sh;
;                     u32x2 w; w.x = pk2(hv[0], hv[1]); w.y = pk2(hv[2], hv[3]); *(u32x2*)(hr + lane * 4 + 256 * j) = w; }
	v_pk_fma_f32 v[12:13], v[64:65], v[32:33], v[12:13]
	v_pk_fma_f32 v[14:15], v[66:67], v[34:35], v[14:15]
	global_store_dwordx4 v160, v[12:15], s[40:41] nt
	v_lshlrev_b32_e32 v32, 16, v52
	v_and_b32_e32 v33, 0xffff0000, v52
	v_lshlrev_b32_e32 v34, 16, v53
	v_and_b32_e32 v35, 0xffff0000, v53
	v_pk_mul_f32 v[32:33], v[32:33], v[164:165] op_sel_hi:[1,0]
	v_pk_mul_f32 v[34:35], v[34:35], v[164:165] op_sel_hi:[1,0]
	v_pk_mul_f32 v[32:33], v[222:223], v[32:33]
	v_pk_mul_f32 v[34:35], v[224:225], v[34:35]
	s_waitcnt vmcnt(23)
	v_pk_fma_f32 v[8:9], v[68:69], v[32:33], v[8:9]
	v_pk_fma_f32 v[10:11], v[70:71], v[34:35], v[10:11]
	global_store_dwordx4 v160, v[8:11], s[40:41] offset:1024 nt
	v_lshlrev_b32_e32 v32, 16, v50
	v_and_b32_e32 v33, 0xffff0000, v50
	v_lshlrev_b32_e32 v34, 16, v51
	v_and_b32_e32 v35, 0xffff0000, v51
	v_pk_mul_f32 v[32:33], v[32:33], v[164:165] op_sel_hi:[1,0]
	v_pk_mul_f32 v[34:35], v[34:35], v[164:165] op_sel_hi:[1,0]
	v_pk_mul_f32 v[32:33], v[226:227], v[32:33]
	v_pk_mul_f32 v[34:35], v[228:229], v[34:35]
	s_waitcnt vmcnt(23)
	v_pk_fma_f32 v[4:5], v[72:73], v[32:33], v[4:5]
	v_pk_fma_f32 v[6:7], v[74:75], v[34:35], v[6:7]
	global_store_dwordx4 v160, v[4:7], s[40:41] offset:2048 nt
	v_lshlrev_b32_e32 v32, 16, v48
	v_and_b32_e32 v33, 0xffff0000, v48
	v_lshlrev_b32_e32 v34, 16, v49
	v_and_b32_e32 v35, 0xffff0000, v49
	v_pk_mul_f32 v[32:33], v[32:33], v[164:165] op_sel_hi:[1,0]
	v_pk_mul_f32 v[34:35], v[34:35], v[164:165] op_sel_hi:[1,0]
	v_pk_mul_f32 v[32:33], v[230:231], v[32:33]
	v_pk_mul_f32 v[34:35], v[232:233], v[34:35]
	s_waitcnt vmcnt(23)
	v_pk_fma_f32 v[0:1], v[76:77], v[32:33], v[0:1]
	v_pk_fma_f32 v[2:3], v[78:79], v[34:35], v[2:3]
	global_store_dwordx4 v160, v[0:3], s[40:41] offset:3072 nt
	global_load_dwordx4 v[64:67], v160, s[50:51]
	global_load_dwordx4 v[68:71], v160, s[50:51] offset:1024
	global_load_dwordx4 v[72:75], v160, s[50:51] offset:2048
	global_load_dwordx4 v[76:79], v160, s[50:51] offset:3072
	v_add_co_u32_e32 v250, vcc, 0xfbc00000, v46
	v_addc_co_u32_e32 v251, vcc, -1, v47, vcc
	v_pk_mul_f32 v[166:167], v[12:13], v[12:13]
	v_pk_mul_f32 v[168:169], v[14:15], v[14:15]
	v_pk_fma_f32 v[166:167], v[8:9], v[8:9], v[166:167]
	v_pk_fma_f32 v[168:169], v[10:11], v[10:11], v[168:169]
	v_pk_fma_f32 v[166:167], v[4:5], v[4:5], v[166:167]
	v_pk_fma_f32 v[168:169], v[6:7], v[6:7], v[168:169]
	v_pk_fma_f32 v[166:167], v[0:1], v[0:1], v[166:167]
	v_pk_fma_f32 v[168:169], v[2:3], v[2:3], v[168:169]
	v_pk_add_f32 v[166:167], v[166:167], v[168:169]
	s_nop 0
	v_add_f32_e32 v164, v166, v167
	v_mov_b32_e32 v165, v164
	s_nop 1
	v_permlane32_swap_b32_e32 v165, v164
	v_add_f32_e32 v164, v164, v165
	v_mov_b32_e32 v165, v164
	s_nop 1
	v_permlane16_swap_b32_e32 v165, v164
	v_add_f32_e32 v164, v164, v165
	s_nop 1
	v_add_f32_dpp v164, v164, v164 row_ror:8 row_mask:0xf bank_mask:0xf
	s_nop 1
	v_add_f32_dpp v164, v164, v164 row_ror:4 row_mask:0xf bank_mask:0xf
	s_nop 1
	v_add_f32_dpp v164, v164, v164 row_ror:2 row_mask:0xf bank_mask:0xf
	s_nop 1
	v_add_f32_dpp v164, v164, v164 row_ror:1 row_mask:0xf bank_mask:0xf
	s_nop 0
	v_fmamk_f32 v164, v164, 0x3a800000, v200
	v_rsq_f32_e32 v164, v164
	s_nop 0
	v_pk_mul_f32 v[12:13], v[12:13], v[164:165] op_sel_hi:[1,0]
	v_pk_mul_f32 v[14:15], v[14:15], v[164:165] op_sel_hi:[1,0]
	v_pk_mul_f32 v[12:13], v[234:235], v[12:13]
	v_pk_mul_f32 v[14:15], v[236:237], v[14:15]
	s_waitcnt vmcnt(15)
	v_pk_add_f32 v[172:173], v[172:173], 1.0 op_sel_hi:[1,0]
	v_pk_add_f32 v[174:175], v[174:175], 1.0 op_sel_hi:[1,0]
	v_pk_fma_f32 v[12:13], v[172:173], v[12:13], v[80:81]
	v_pk_fma_f32 v[14:15], v[174:175], v[14:15], v[82:83]
	v_cvt_pk_bf16_f32 v12, v12, v13
	v_cvt_pk_bf16_f32 v13, v14, v15
	global_store_dwordx2 v[250:251], v[12:13], off offset:-1536
	global_load_dwordx4 v[80:83], v160, s[52:53]
	v_pk_mul_f32 v[8:9], v[8:9], v[164:165] op_sel_hi:[1,0]
	v_pk_mul_f32 v[10:11], v[10:11], v[164:165] op_sel_hi:[1,0]
	v_pk_mul_f32 v[8:9], v[238:239], v[8:9]
	v_pk_mul_f32 v[10:11], v[240:241], v[10:11]
	s_waitcnt vmcnt(16)
	v_pk_add_f32 v[176:177], v[176:177], 1.0 op_sel_hi:[1,0]
	v_pk_add_f32 v[178:179], v[178:179], 1.0 op_sel_hi:[1,0]
	v_pk_fma_f32 v[8:9], v[176:177], v[8:9], v[84:85]
	v_pk_fma_f32 v[10:11], v[178:179], v[10:11], v[86:87]
	v_cvt_pk_bf16_f32 v8, v8, v9
	v_cvt_pk_bf16_f32 v9, v10, v11
	global_store_dwordx2 v[250:251], v[8:9], off offset:-1024
	global_load_dwordx4 v[84:87], v160, s[52:53] offset:1024
	v_pk_mul_f32 v[4:5], v[4:5], v[164:165] op_sel_hi:[1,0]
	v_pk_mul_f32 v[6:7], v[6:7], v[164:165] op_sel_hi:[1,0]
	v_pk_mul_f32 v[4:5], v[242:243], v[4:5]
	v_pk_mul_f32 v[6:7], v[244:245], v[6:7]
	s_waitcnt vmcnt(17)
	v_pk_add_f32 v[180:181], v[180:181], 1.0 op_sel_hi:[1,0]
	v_pk_add_f32 v[182:183], v[182:183], 1.0 op_sel_hi:[1,0]
	v_pk_fma_f32 v[4:5], v[180:181], v[4:5], v[88:89]
	v_pk_fma_f32 v[6:7], v[182:183], v[6:7], v[90:91]
	v_cvt_pk_bf16_f32 v4, v4, v5
	v_cvt_pk_bf16_f32 v5, v6, v7
	global_store_dwordx2 v[250:251], v[4:5], off offset:-512
	global_load_dwordx4 v[88:91], v160, s[52:53] offset:2048
	v_pk_mul_f32 v[0:1], v[0:1], v[164:165] op_sel_hi:[1,0]
	v_pk_mul_f32 v[2:3], v[2:3], v[164:165] op_sel_hi:[1,0]
	v_pk_mul_f32 v[0:1], v[246:247], v[0:1]
	v_pk_mul_f32 v[2:3], v[248:249], v[2:3]
	s_waitcnt vmcnt(18)
	v_pk_add_f32 v[184:185], v[184:185], 1.0 op_sel_hi:[1,0]
	v_pk_add_f32 v[186:187], v[186:187], 1.0 op_sel_hi:[1,0]
	v_pk_fma_f32 v[0:1], v[184:185], v[0:1], v[92:93]
	v_pk_fma_f32 v[2:3], v[186:187], v[2:3], v[94:95]
	v_cvt_pk_bf16_f32 v0, v0, v1
	v_cvt_pk_bf16_f32 v1, v2, v3
	global_store_dwordx2 v[250:251], v[0:1], off
	global_load_dwordx4 v[92:95], v160, s[52:53] offset:3072
	s_waitcnt vmcnt(28)
; __device__ __forceinline__ float bflo(unsigned w) { return __uint_as_float(w << 16); }
; __device__ __forceinline__ float bfhi(unsigned w) { return __uint_as_float(w & 0xffff0000u); }
;     __device__ __forceinline__ void init(int N, int G, int c, int latent_only) { lat = latent_only; b.init(latent_only ? NB * SEQ : M, N, G, c); }
;     __device__ __forceinline__ void init(int c_, unsigned* cnt_) { lat.init(NB * SEQ, FF2, 1, 0); c = c_; cnt = cnt_; }
; __device__ __forceinline__ void row_pass(const RowPass& R, int gw, int ngw, int lane) {
;     ...
;             if (R.update) {
;                 f32x4 y[4]; float ss = 0.f;
; #pragma unroll
;                 for (int j = 0; j < 4; ++j) { const u32x2 w = yw[k][j]; y[j] = (f32x4){bflo(w.x), bfhi(w.x), bflo(w.y), bfhi(w.y)};
;                     ss += (y[j][0] * y[j][0] + y[j][1] * y[j][1]) + (y[j][2] * y[j][2] + y[j][3] * y[j][3]); }
;                 const float rstd = __builtin_amdgcn_rsqf(wave_sum(ss) * (1.0f / DM) + EPS);
;                 const float* gate = R.mod + ((size_t)(R.lg * 9 + bb) * NMOD + R.gi) * DM;
; #pragma unroll
;                 for (int j = 0; j < 4; ++j) { const f32x4 g = *(const f32x4*)(gate + lane * 4 + 256 * j), gp = *(const f32x4*)(R.gpost + lane * 4 + 256 * j);
;                     v[k][j] = v[k][j] + g * (y[j] * rstd * gp); }
;             }
;             if (R.init || R.update) {
; #pragma unroll
;                 for (int j = 0; j < 4; ++j) __builtin_nontemporal_store(v[k][j], (f32x4*)(xrow[k] + lane * 4 + 256 * j));
	v_lshlrev_b32_e32 v32, 16, v62
	v_and_b32_e32 v33, 0xffff0000, v62
	v_lshlrev_b32_e32 v34, 16, v63
	v_and_b32_e32 v35, 0xffff0000, v63
	v_pk_mul_f32 v[166:167], v[32:33], v[32:33]
	v_pk_mul_f32 v[168:169], v[34:35], v[34:35]
	v_lshlrev_b32_e32 v32, 16, v60
	v_and_b32_e32 v33, 0xffff0000, v60
	v_lshlrev_b32_e32 v34, 16, v61
	v_and_b32_e32 v35, 0xffff0000, v61
	v_pk_fma_f32 v[166:167], v[32:33], v[32:33], v[166:167]
	v_pk_fma_f32 v[168:169], v[34:35], v[34:35], v[168:169]
	v_lshlrev_b32_e32 v32, 16, v58
	v_and_b32_e32 v33, 0xffff0000, v58
	v_lshlrev_b32_e32 v34, 16, v59
	v_and_b32_e32 v35, 0xffff0000, v59
	v_pk_fma_f32 v[166:167], v[32:33], v[32:33], v[166:167]
	v_pk_fma_f32 v[168:169], v[34:35], v[34:35], v[168:169]
	v_lshlrev_b32_e32 v32, 16, v56
	v_and_b32_e32 v33, 0xffff0000, v56
	v_lshlrev_b32_e32 v34, 16, v57
	v_and_b32_e32 v35, 0xffff0000, v57
	v_pk_fma_f32 v[166:167], v[32:33], v[32:33], v[166:167]
	v_pk_fma_f32 v[168:169], v[34:35], v[34:35], v[168:169]
	v_pk_add_f32 v[166:167], v[166:167], v[168:169]
	s_nop 0
	v_add_f32_e32 v164, v166, v167
	v_mov_b32_e32 v165, v164
	s_nop 1
	v_permlane32_swap_b32_e32 v165, v164
	v_add_f32_e32 v164, v164, v165
	v_mov_b32_e32 v165, v164
	s_nop 1
	v_permlane16_swap_b32_e32 v165, v164
	v_add_f32_e32 v164, v164, v165
	s_nop 1
	v_add_f32_dpp v164, v164, v164 row_ror:8 row_mask:0xf bank_mask:0xf
	s_nop 1
	v_add_f32_dpp v164, v164, v164 row_ror:4 row_mask:0xf bank_mask:0xf
	s_nop 1
	v_add_f32_dpp v164, v164, v164 row_ror:2 row_mask:0xf bank_mask:0xf
	s_nop 1
	v_add_f32_dpp v164, v164, v164 row_ror:1 row_mask:0xf bank_mask:0xf
	s_nop 0
	v_fmamk_f32 v164, v164, 0x3a800000, v200
	v_rsq_f32_e32 v164, v164
	v_lshlrev_b32_e32 v32, 16, v62
	v_and_b32_e32 v33, 0xffff0000, v62
	v_lshlrev_b32_e32 v34, 16, v63
	v_and_b32_e32 v35, 0xffff0000, v63
	v_pk_mul_f32 v[32:33], v[32:33], v[164:165] op_sel_hi:[1,0]
	v_pk_mul_f32 v[34:35], v[34:35], v[164:165] op_sel_hi:[1,0]
	v_pk_mul_f32 v[32:33], v[218:219], v[32:33]
	v_pk_mul_f32 v[34:35], v[220:221], v[34:35]
	s_waitcnt vmcnt(19)
	v_pk_fma_f32 v[16:17], v[188:189], v[32:33], v[16:17]
	v_pk_fma_f32 v[18:19], v[190:191], v[34:35], v[18:19]
	global_store_dwordx4 v160, v[16:19], s[64:65] nt
	v_lshlrev_b32_e32 v32, 16, v60
	v_and_b32_e32 v33, 0xffff0000, v60
	v_lshlrev_b32_e32 v34, 16, v61
	v_and_b32_e32 v35, 0xffff0000, v61
	v_pk_mul_f32 v[32:33], v[32:33], v[164:165] op_sel_hi:[1,0]
	v_pk_mul_f32 v[34:35], v[34:35], v[164:165] op_sel_hi:[1,0]
	v_pk_mul_f32 v[32:33], v[222:223], v[32:33]
	v_pk_mul_f32 v[34:35], v[224:225], v[34:35]
	s_waitcnt vmcnt(19)
	v_pk_fma_f32 v[20:21], v[192:193], v[32:33], v[20:21]
	v_pk_fma_f32 v[22:23], v[194:195], v[34:35], v[22:23]
	global_store_dwordx4 v160, v[20:23], s[64:65] offset:1024 nt
	v_lshlrev_b32_e32 v32, 16, v58
	v_and_b32_e32 v33, 0xffff0000, v58
	v_lshlrev_b32_e32 v34, 16, v59
	v_and_b32_e32 v35, 0xffff0000, v59
	v_pk_mul_f32 v[32:33], v[32:33], v[164:165] op_sel_hi:[1,0]
	v_pk_mul_f32 v[34:35], v[34:35], v[164:165] op_sel_hi:[1,0]
	v_pk_mul_f32 v[32:33], v[226:227], v[32:33]
	v_pk_mul_f32 v[34:35], v[228:229], v[34:35]
	s_waitcnt vmcnt(19)
	v_pk_fma_f32 v[24:25], v[196:197], v[32:33], v[24:25]
	v_pk_fma_f32 v[26:27], v[198:199], v[34:35], v[26:27]
	global_store_dwordx4 v160, v[24:27], s[64:65] offset:2048 nt
	v_lshlrev_b32_e32 v32, 16, v56
	v_and_b32_e32 v33, 0xffff0000, v56
	v_lshlrev_b32_e32 v34, 16, v57
	v_and_b32_e32 v35, 0xffff0000, v57
	v_pk_mul_f32 v[32:33], v[32:33], v[164:165] op_sel_hi:[1,0]
	v_pk_mul_f32 v[34:35], v[34:35], v[164:165] op_sel_hi:[1,0]
	v_pk_mul_f32 v[32:33], v[230:231], v[32:33]
	v_pk_mul_f32 v[34:35], v[232:233], v[34:35]
	s_waitcnt vmcnt(19)
; __device__ __forceinline__ unsigned pk2(float lo, float hi) { return pg8::cvt_pk_bf16(lo, hi); }
; __device__ __forceinline__ void row_pass(const RowPass& R, int gw, int ngw, int lane) {
;     ...
;             if (R.norm_out) {
;                 float ss = 0.f;
; #pragma unroll
;                 for (int j = 0; j < 4; ++j) ss += (v[k][j][0] * v[k][j][0] + v[k][j][1] * v[k][j][1]) + (v[k][j][2] * v[k][j][2] + v[k][j][3] * v[k][j][3]);
;                 const float rstd = __builtin_amdgcn_rsqf(wave_sum(ss) * (1.0f / DM) + EPS);
;                 const float* shift = R.mod + ((size_t)(R.ln * 9 + bb) * NMOD + R.si) * DM; const float* scale = shift + DM;
;                 bf16* hr = R.H + (size_t)row * DM;
; #pragma unroll
;                 for (int j = 0; j < 4; ++j) { const f32x4 gp = *(const f32x4*)(R.gpre + lane * 4 + 256 * j), sh = *(const f32x4*)(shift + lane * 4 + 256 * j), sc = *(const f32x4*)(scale + lane * 4 + 256 * j);
;                     const f32x4 hv = (v[k][j] * rstd * gp) * (sc + 1.0f) + sh;
;                     u32x2 w; w.x = pk2(hv[0], hv[1]); w.y = pk2(hv[2], hv[3]); *(u32x2*)(hr + lane * 4 + 256 * j) = w; }
	v_pk_fma_f32 v[28:29], v[96:97], v[32:33], v[28:29]
	v_pk_fma_f32 v[30:31], v[98:99], v[34:35], v[30:31]
	global_store_dwordx4 v160, v[28:31], s[64:65] offset:3072 nt
	v_pk_mul_f32 v[166:167], v[16:17], v[16:17]
	v_pk_mul_f32 v[168:169], v[18:19], v[18:19]
	v_pk_fma_f32 v[166:167], v[20:21], v[20:21], v[166:167]
	v_pk_fma_f32 v[168:169], v[22:23], v[22:23], v[168:169]
	v_pk_fma_f32 v[166:167], v[24:25], v[24:25], v[166:167]
	v_pk_fma_f32 v[168:169], v[26:27], v[26:27], v[168:169]
	v_pk_fma_f32 v[166:167], v[28:29], v[28:29], v[166:167]
	v_pk_fma_f32 v[168:169], v[30:31], v[30:31], v[168:169]
	v_pk_add_f32 v[166:167], v[166:167], v[168:169]
	s_nop 0
	v_add_f32_e32 v164, v166, v167
	v_mov_b32_e32 v165, v164
	s_nop 1
	v_permlane32_swap_b32_e32 v165, v164
	v_add_f32_e32 v164, v164, v165
	v_mov_b32_e32 v165, v164
	s_nop 1
	v_permlane16_swap_b32_e32 v165, v164
	v_add_f32_e32 v164, v164, v165
	s_nop 1
	v_add_f32_dpp v164, v164, v164 row_ror:8 row_mask:0xf bank_mask:0xf
	s_nop 1
	v_add_f32_dpp v164, v164, v164 row_ror:4 row_mask:0xf bank_mask:0xf
	s_nop 1
	v_add_f32_dpp v164, v164, v164 row_ror:2 row_mask:0xf bank_mask:0xf
	s_nop 1
	v_add_f32_dpp v164, v164, v164 row_ror:1 row_mask:0xf bank_mask:0xf
	s_nop 0
	v_fmamk_f32 v164, v164, 0x3a800000, v200
	v_rsq_f32_e32 v164, v164
	s_nop 0
	v_pk_mul_f32 v[16:17], v[16:17], v[164:165] op_sel_hi:[1,0]
	v_pk_mul_f32 v[18:19], v[18:19], v[164:165] op_sel_hi:[1,0]
	v_pk_mul_f32 v[16:17], v[234:235], v[16:17]
	v_pk_mul_f32 v[18:19], v[236:237], v[18:19]
	s_waitcnt vmcnt(10)
	v_pk_add_f32 v[80:81], v[80:81], 1.0 op_sel_hi:[1,0]
	v_pk_add_f32 v[82:83], v[82:83], 1.0 op_sel_hi:[1,0]
	v_pk_fma_f32 v[16:17], v[80:81], v[16:17], v[64:65]
	v_pk_fma_f32 v[18:19], v[82:83], v[18:19], v[66:67]
	v_cvt_pk_bf16_f32 v16, v16, v17
	v_cvt_pk_bf16_f32 v17, v18, v19
	global_store_dwordx2 v[252:253], v[16:17], off
	v_pk_mul_f32 v[20:21], v[20:21], v[164:165] op_sel_hi:[1,0]
	v_pk_mul_f32 v[22:23], v[22:23], v[164:165] op_sel_hi:[1,0]
	v_pk_mul_f32 v[20:21], v[238:239], v[20:21]
	v_pk_mul_f32 v[22:23], v[240:241], v[22:23]
	s_waitcnt vmcnt(9)
	v_pk_add_f32 v[84:85], v[84:85], 1.0 op_sel_hi:[1,0]
	v_pk_add_f32 v[86:87], v[86:87], 1.0 op_sel_hi:[1,0]
	v_pk_fma_f32 v[20:21], v[84:85], v[20:21], v[68:69]
	v_pk_fma_f32 v[22:23], v[86:87], v[22:23], v[70:71]
	v_cvt_pk_bf16_f32 v20, v20, v21
	v_cvt_pk_bf16_f32 v21, v22, v23
	global_store_dwordx2 v[252:253], v[20:21], off offset:512
	v_pk_mul_f32 v[24:25], v[24:25], v[164:165] op_sel_hi:[1,0]
	v_pk_mul_f32 v[26:27], v[26:27], v[164:165] op_sel_hi:[1,0]
	v_pk_mul_f32 v[24:25], v[242:243], v[24:25]
	v_pk_mul_f32 v[26:27], v[244:245], v[26:27]
	s_waitcnt vmcnt(8)
	v_pk_add_f32 v[88:89], v[88:89], 1.0 op_sel_hi:[1,0]
	v_pk_add_f32 v[90:91], v[90:91], 1.0 op_sel_hi:[1,0]
	v_pk_fma_f32 v[24:25], v[88:89], v[24:25], v[72:73]
	v_pk_fma_f32 v[26:27], v[90:91], v[26:27], v[74:75]
	v_cvt_pk_bf16_f32 v24, v24, v25
	v_cvt_pk_bf16_f32 v25, v26, v27
	global_store_dwordx2 v[252:253], v[24:25], off offset:1024
	v_pk_mul_f32 v[28:29], v[28:29], v[164:165] op_sel_hi:[1,0]
	v_pk_mul_f32 v[30:31], v[30:31], v[164:165] op_sel_hi:[1,0]
	v_pk_mul_f32 v[28:29], v[246:247], v[28:29]
	v_pk_mul_f32 v[30:31], v[248:249], v[30:31]
	s_waitcnt vmcnt(7)
	v_pk_add_f32 v[92:93], v[92:93], 1.0 op_sel_hi:[1,0]
	v_pk_add_f32 v[94:95], v[94:95], 1.0 op_sel_hi:[1,0]
	v_pk_fma_f32 v[28:29], v[92:93], v[28:29], v[76:77]
	v_pk_fma_f32 v[30:31], v[94:95], v[30:31], v[78:79]
	v_cvt_pk_bf16_f32 v28, v28, v29
	v_cvt_pk_bf16_f32 v29, v30, v31
	global_store_dwordx2 v[252:253], v[28:29], off offset:1536
	s_branch .LBB0_148
